# v19 plus lean phase-11 epilogue: clamp/rndne/cvt_i32 replaced by one f32 add of 2^23 with byte select (provably unclipped rows only), 256 fewer VALU per tile
# speedup vs baseline: 1.0004x; 1.0004x over previous
.Llean_p11:
	v_max3_i32 v228, v124, v125, v126
	v_max3_i32 v228, v228, v127, v120
	v_max3_i32 v228, v228, v121, v122
	v_max3_i32 v228, v228, v123, v116
	v_max3_i32 v228, v228, v117, v118
	v_max3_i32 v228, v228, v119, v112
	v_max3_i32 v228, v228, v113, v114
	v_max_i32_e32 v228, v228, v115
	v_cmp_ge_i32_e32 vcc, v228, v233
	v_max3_i32 v228, v108, v109, v110
	v_max3_i32 v228, v228, v111, v104
	v_max3_i32 v228, v228, v105, v106
	v_max3_i32 v228, v228, v107, v100
	v_max3_i32 v228, v228, v101, v102
	v_max3_i32 v228, v228, v103, v96
	v_max3_i32 v228, v228, v97, v98
	v_max_i32_e32 v228, v228, v99
	v_cmp_ge_i32_e64 s[96:97], v228, v235
	s_or_b64 vcc, vcc, s[96:97]
	v_max3_i32 v228, v92, v93, v94
	v_max3_i32 v228, v228, v95, v88
	v_max3_i32 v228, v228, v89, v90
	v_max3_i32 v228, v228, v91, v84
	v_max3_i32 v228, v228, v85, v86
	v_max3_i32 v228, v228, v87, v80
	v_max3_i32 v228, v228, v81, v82
	v_max_i32_e32 v228, v228, v83
	v_cmp_ge_i32_e64 s[96:97], v228, v237
	s_or_b64 vcc, vcc, s[96:97]
	v_max3_i32 v228, v76, v77, v78
	v_max3_i32 v228, v228, v79, v72
	v_max3_i32 v228, v228, v73, v74
	v_max3_i32 v228, v228, v75, v68
	v_max3_i32 v228, v228, v69, v70
	v_max3_i32 v228, v228, v71, v64
	v_max3_i32 v228, v228, v65, v66
	v_max_i32_e32 v228, v228, v67
	v_cmp_ge_i32_e64 s[96:97], v228, v239
	s_or_b64 vcc, vcc, s[96:97]
	v_max3_i32 v228, v60, v61, v62
	v_max3_i32 v228, v228, v63, v56
	v_max3_i32 v228, v228, v57, v58
	v_max3_i32 v228, v228, v59, v52
	v_max3_i32 v228, v228, v53, v54
	v_max3_i32 v228, v228, v55, v48
	v_max3_i32 v228, v228, v49, v50
	v_max_i32_e32 v228, v228, v51
	v_cmp_ge_i32_e64 s[96:97], v228, v241
	s_or_b64 vcc, vcc, s[96:97]
	v_max3_i32 v228, v44, v45, v46
	v_max3_i32 v228, v228, v47, v40
	v_max3_i32 v228, v228, v41, v42
	v_max3_i32 v228, v228, v43, v36
	v_max3_i32 v228, v228, v37, v38
	v_max3_i32 v228, v228, v39, v32
	v_max3_i32 v228, v228, v33, v34
	v_max_i32_e32 v228, v228, v35
	v_cmp_ge_i32_e64 s[96:97], v228, v243
	s_or_b64 vcc, vcc, s[96:97]
	v_max3_i32 v228, v28, v29, v30
	v_max3_i32 v228, v228, v31, v24
	v_max3_i32 v228, v228, v25, v26
	v_max3_i32 v228, v228, v27, v20
	v_max3_i32 v228, v228, v21, v22
	v_max3_i32 v228, v228, v23, v16
	v_max3_i32 v228, v228, v17, v18
	v_max_i32_e32 v228, v228, v19
	v_cmp_ge_i32_e64 s[96:97], v228, v245
	s_or_b64 vcc, vcc, s[96:97]
	v_max3_i32 v228, v12, v13, v14
	v_max3_i32 v228, v228, v15, v8
	v_max3_i32 v228, v228, v9, v10
	v_max3_i32 v228, v228, v11, v4
	v_max3_i32 v228, v228, v5, v6
	v_max3_i32 v228, v228, v7, v0
	v_max3_i32 v228, v228, v1, v2
	v_max_i32_e32 v228, v228, v3
	v_cmp_ge_i32_e64 s[96:97], v228, v247
	s_or_b64 vcc, vcc, s[96:97]
	s_cbranch_vccnz .Lorig_p11
	v_mov_b32_e32 v228, 0x4b000000
	v_lshl_add_u32 v146, s28, 8, v177
	v_mov_b32_e32 v147, 0
	v_lshl_or_b32 v148, s0, 8, v179
	v_mov_b32_e32 v149, 0
	v_lshlrev_b64 v[146:147], 14, v[146:147]
	v_lshl_add_u64 v[146:147], s[10:11], 0, v[146:147]
	v_lshl_add_u64 v[150:151], v[146:147], 0, v[148:149]
	v_mov_b32_e32 v154, 0x41700000
	v_mov_b32_e32 v155, 0x41700000
	v_cvt_f32_i32_e32 v124, v124
	v_cvt_f32_i32_e32 v125, v125
	v_cvt_f32_i32_e32 v126, v126
	v_cvt_f32_i32_e32 v127, v127
	v_cvt_f32_i32_e32 v120, v120
	v_cvt_f32_i32_e32 v121, v121
	v_cvt_f32_i32_e32 v122, v122
	v_cvt_f32_i32_e32 v123, v123
	v_pk_mul_f32 v[124:125], v[232:233], v[124:125] op_sel_hi:[0,1]
	v_pk_mul_f32 v[126:127], v[232:233], v[126:127] op_sel_hi:[0,1]
	v_pk_mul_f32 v[120:121], v[232:233], v[120:121] op_sel_hi:[0,1]
	v_pk_mul_f32 v[122:123], v[232:233], v[122:123] op_sel_hi:[0,1]
	v_max_f32_e32 v124, 0, v124
	v_max_f32_e32 v125, 0, v125
	v_max_f32_e32 v126, 0, v126
	v_max_f32_e32 v127, 0, v127
	v_max_f32_e32 v120, 0, v120
	v_max_f32_e32 v121, 0, v121
	v_max_f32_e32 v122, 0, v122
	v_max_f32_e32 v123, 0, v123
	v_pk_mul_f32 v[124:125], v[124:125], v[124:125]
	v_pk_mul_f32 v[126:127], v[126:127], v[126:127]
	v_pk_mul_f32 v[120:121], v[120:121], v[120:121]
	v_pk_mul_f32 v[122:123], v[122:123], v[122:123]
	v_pk_mul_f32 v[124:125], v[154:155], v[124:125]
	v_pk_mul_f32 v[126:127], v[154:155], v[126:127]
	v_pk_mul_f32 v[120:121], v[154:155], v[120:121]
	v_pk_mul_f32 v[122:123], v[154:155], v[122:123]
	v_add_f32_e32 v186, v228, v124
	v_add_f32_e32 v187, v228, v120
	v_add_f32_sdwa v186, v125, v228 dst_sel:BYTE_1 dst_unused:UNUSED_PRESERVE src0_sel:DWORD src1_sel:DWORD
	v_add_f32_sdwa v187, v121, v228 dst_sel:BYTE_1 dst_unused:UNUSED_PRESERVE src0_sel:DWORD src1_sel:DWORD
	v_add_f32_sdwa v186, v126, v228 dst_sel:BYTE_2 dst_unused:UNUSED_PRESERVE src0_sel:DWORD src1_sel:DWORD
	v_add_f32_sdwa v187, v122, v228 dst_sel:BYTE_2 dst_unused:UNUSED_PRESERVE src0_sel:DWORD src1_sel:DWORD
	v_add_f32_sdwa v186, v127, v228 dst_sel:BYTE_3 dst_unused:UNUSED_PRESERVE src0_sel:DWORD src1_sel:DWORD
	v_add_f32_sdwa v187, v123, v228 dst_sel:BYTE_3 dst_unused:UNUSED_PRESERVE src0_sel:DWORD src1_sel:DWORD
	v_xor_b32_e32 v186, s55, v186
	v_xor_b32_e32 v187, s55, v187
	global_store_dwordx2 v[150:151], v[186:187], off
	v_cvt_f32_i32_e32 v116, v116
	v_cvt_f32_i32_e32 v117, v117
	v_cvt_f32_i32_e32 v118, v118
	v_cvt_f32_i32_e32 v119, v119
	v_cvt_f32_i32_e32 v112, v112
	v_cvt_f32_i32_e32 v113, v113
	v_cvt_f32_i32_e32 v114, v114
	v_cvt_f32_i32_e32 v115, v115
	v_pk_mul_f32 v[116:117], v[232:233], v[116:117] op_sel_hi:[0,1]
	v_pk_mul_f32 v[118:119], v[232:233], v[118:119] op_sel_hi:[0,1]
	v_pk_mul_f32 v[112:113], v[232:233], v[112:113] op_sel_hi:[0,1]
	v_pk_mul_f32 v[114:115], v[232:233], v[114:115] op_sel_hi:[0,1]
	v_max_f32_e32 v116, 0, v116
	v_max_f32_e32 v117, 0, v117
	v_max_f32_e32 v118, 0, v118
	v_max_f32_e32 v119, 0, v119
	v_max_f32_e32 v112, 0, v112
	v_max_f32_e32 v113, 0, v113
	v_max_f32_e32 v114, 0, v114
	v_max_f32_e32 v115, 0, v115
	v_pk_mul_f32 v[116:117], v[116:117], v[116:117]
	v_pk_mul_f32 v[118:119], v[118:119], v[118:119]
	v_pk_mul_f32 v[112:113], v[112:113], v[112:113]
	v_pk_mul_f32 v[114:115], v[114:115], v[114:115]
	v_pk_mul_f32 v[116:117], v[154:155], v[116:117]
	v_pk_mul_f32 v[118:119], v[154:155], v[118:119]
	v_pk_mul_f32 v[112:113], v[154:155], v[112:113]
	v_pk_mul_f32 v[114:115], v[154:155], v[114:115]
	v_add_f32_e32 v188, v228, v116
	v_add_f32_e32 v189, v228, v112
	v_add_f32_sdwa v188, v117, v228 dst_sel:BYTE_1 dst_unused:UNUSED_PRESERVE src0_sel:DWORD src1_sel:DWORD
	v_add_f32_sdwa v189, v113, v228 dst_sel:BYTE_1 dst_unused:UNUSED_PRESERVE src0_sel:DWORD src1_sel:DWORD
	v_add_f32_sdwa v188, v118, v228 dst_sel:BYTE_2 dst_unused:UNUSED_PRESERVE src0_sel:DWORD src1_sel:DWORD
	v_add_f32_sdwa v189, v114, v228 dst_sel:BYTE_2 dst_unused:UNUSED_PRESERVE src0_sel:DWORD src1_sel:DWORD
	v_add_f32_sdwa v188, v119, v228 dst_sel:BYTE_3 dst_unused:UNUSED_PRESERVE src0_sel:DWORD src1_sel:DWORD
	v_add_f32_sdwa v189, v115, v228 dst_sel:BYTE_3 dst_unused:UNUSED_PRESERVE src0_sel:DWORD src1_sel:DWORD
	v_xor_b32_e32 v188, s55, v188
	v_xor_b32_e32 v189, s55, v189
	global_store_dwordx2 v[150:151], v[188:189], off offset:128
	v_add_co_u32_e32 v152, vcc, 0x40000, v150
	s_nop 1
	v_addc_co_u32_e32 v153, vcc, 0, v151, vcc
	v_cvt_f32_i32_e32 v108, v108
	v_cvt_f32_i32_e32 v109, v109
	v_cvt_f32_i32_e32 v110, v110
	v_cvt_f32_i32_e32 v111, v111
	v_cvt_f32_i32_e32 v104, v104
	v_cvt_f32_i32_e32 v105, v105
	v_cvt_f32_i32_e32 v106, v106
	v_cvt_f32_i32_e32 v107, v107
	v_pk_mul_f32 v[108:109], v[234:235], v[108:109] op_sel_hi:[0,1]
	v_pk_mul_f32 v[110:111], v[234:235], v[110:111] op_sel_hi:[0,1]
	v_pk_mul_f32 v[104:105], v[234:235], v[104:105] op_sel_hi:[0,1]
	v_pk_mul_f32 v[106:107], v[234:235], v[106:107] op_sel_hi:[0,1]
	v_max_f32_e32 v108, 0, v108
	v_max_f32_e32 v109, 0, v109
	v_max_f32_e32 v110, 0, v110
	v_max_f32_e32 v111, 0, v111
	v_max_f32_e32 v104, 0, v104
	v_max_f32_e32 v105, 0, v105
	v_max_f32_e32 v106, 0, v106
	v_max_f32_e32 v107, 0, v107
	v_pk_mul_f32 v[108:109], v[108:109], v[108:109]
	v_pk_mul_f32 v[110:111], v[110:111], v[110:111]
	v_pk_mul_f32 v[104:105], v[104:105], v[104:105]
	v_pk_mul_f32 v[106:107], v[106:107], v[106:107]
	v_pk_mul_f32 v[108:109], v[154:155], v[108:109]
	v_pk_mul_f32 v[110:111], v[154:155], v[110:111]
	v_pk_mul_f32 v[104:105], v[154:155], v[104:105]
	v_pk_mul_f32 v[106:107], v[154:155], v[106:107]
	v_add_f32_e32 v190, v228, v108
	v_add_f32_e32 v191, v228, v104
	v_add_f32_sdwa v190, v109, v228 dst_sel:BYTE_1 dst_unused:UNUSED_PRESERVE src0_sel:DWORD src1_sel:DWORD
	v_add_f32_sdwa v191, v105, v228 dst_sel:BYTE_1 dst_unused:UNUSED_PRESERVE src0_sel:DWORD src1_sel:DWORD
	v_add_f32_sdwa v190, v110, v228 dst_sel:BYTE_2 dst_unused:UNUSED_PRESERVE src0_sel:DWORD src1_sel:DWORD
	v_add_f32_sdwa v191, v106, v228 dst_sel:BYTE_2 dst_unused:UNUSED_PRESERVE src0_sel:DWORD src1_sel:DWORD
	v_add_f32_sdwa v190, v111, v228 dst_sel:BYTE_3 dst_unused:UNUSED_PRESERVE src0_sel:DWORD src1_sel:DWORD
	v_add_f32_sdwa v191, v107, v228 dst_sel:BYTE_3 dst_unused:UNUSED_PRESERVE src0_sel:DWORD src1_sel:DWORD
	v_xor_b32_e32 v190, s55, v190
	v_xor_b32_e32 v191, s55, v191
	global_store_dwordx2 v[152:153], v[190:191], off
	v_cvt_f32_i32_e32 v100, v100
	v_cvt_f32_i32_e32 v101, v101
	v_cvt_f32_i32_e32 v102, v102
	v_cvt_f32_i32_e32 v103, v103
	v_cvt_f32_i32_e32 v96, v96
	v_cvt_f32_i32_e32 v97, v97
	v_cvt_f32_i32_e32 v98, v98
	v_cvt_f32_i32_e32 v99, v99
	v_pk_mul_f32 v[100:101], v[234:235], v[100:101] op_sel_hi:[0,1]
	v_pk_mul_f32 v[102:103], v[234:235], v[102:103] op_sel_hi:[0,1]
	v_pk_mul_f32 v[96:97], v[234:235], v[96:97] op_sel_hi:[0,1]
	v_pk_mul_f32 v[98:99], v[234:235], v[98:99] op_sel_hi:[0,1]
	v_max_f32_e32 v100, 0, v100
	v_max_f32_e32 v101, 0, v101
	v_max_f32_e32 v102, 0, v102
	v_max_f32_e32 v103, 0, v103
	v_max_f32_e32 v96, 0, v96
	v_max_f32_e32 v97, 0, v97
	v_max_f32_e32 v98, 0, v98
	v_max_f32_e32 v99, 0, v99
	v_pk_mul_f32 v[100:101], v[100:101], v[100:101]
	v_pk_mul_f32 v[102:103], v[102:103], v[102:103]
	v_pk_mul_f32 v[96:97], v[96:97], v[96:97]
	v_pk_mul_f32 v[98:99], v[98:99], v[98:99]
	v_pk_mul_f32 v[100:101], v[154:155], v[100:101]
	v_pk_mul_f32 v[102:103], v[154:155], v[102:103]
	v_pk_mul_f32 v[96:97], v[154:155], v[96:97]
	v_pk_mul_f32 v[98:99], v[154:155], v[98:99]
	v_add_f32_e32 v192, v228, v100
	v_add_f32_e32 v193, v228, v96
	v_add_f32_sdwa v192, v101, v228 dst_sel:BYTE_1 dst_unused:UNUSED_PRESERVE src0_sel:DWORD src1_sel:DWORD
	v_add_f32_sdwa v193, v97, v228 dst_sel:BYTE_1 dst_unused:UNUSED_PRESERVE src0_sel:DWORD src1_sel:DWORD
	v_add_f32_sdwa v192, v102, v228 dst_sel:BYTE_2 dst_unused:UNUSED_PRESERVE src0_sel:DWORD src1_sel:DWORD
	v_add_f32_sdwa v193, v98, v228 dst_sel:BYTE_2 dst_unused:UNUSED_PRESERVE src0_sel:DWORD src1_sel:DWORD
	v_add_f32_sdwa v192, v103, v228 dst_sel:BYTE_3 dst_unused:UNUSED_PRESERVE src0_sel:DWORD src1_sel:DWORD
	v_add_f32_sdwa v193, v99, v228 dst_sel:BYTE_3 dst_unused:UNUSED_PRESERVE src0_sel:DWORD src1_sel:DWORD
	v_xor_b32_e32 v192, s55, v192
	v_xor_b32_e32 v193, s55, v193
	global_store_dwordx2 v[152:153], v[192:193], off offset:128
	v_add_co_u32_e32 v152, vcc, 0x80000, v150
	s_nop 1
	v_addc_co_u32_e32 v153, vcc, 0, v151, vcc
	v_cvt_f32_i32_e32 v92, v92
	v_cvt_f32_i32_e32 v93, v93
	v_cvt_f32_i32_e32 v94, v94
	v_cvt_f32_i32_e32 v95, v95
	v_cvt_f32_i32_e32 v88, v88
	v_cvt_f32_i32_e32 v89, v89
	v_cvt_f32_i32_e32 v90, v90
	v_cvt_f32_i32_e32 v91, v91
	v_pk_mul_f32 v[92:93], v[236:237], v[92:93] op_sel_hi:[0,1]
	v_pk_mul_f32 v[94:95], v[236:237], v[94:95] op_sel_hi:[0,1]
	v_pk_mul_f32 v[88:89], v[236:237], v[88:89] op_sel_hi:[0,1]
	v_pk_mul_f32 v[90:91], v[236:237], v[90:91] op_sel_hi:[0,1]
	v_max_f32_e32 v92, 0, v92
	v_max_f32_e32 v93, 0, v93
	v_max_f32_e32 v94, 0, v94
	v_max_f32_e32 v95, 0, v95
	v_max_f32_e32 v88, 0, v88
	v_max_f32_e32 v89, 0, v89
	v_max_f32_e32 v90, 0, v90
	v_max_f32_e32 v91, 0, v91
	v_pk_mul_f32 v[92:93], v[92:93], v[92:93]
	v_pk_mul_f32 v[94:95], v[94:95], v[94:95]
	v_pk_mul_f32 v[88:89], v[88:89], v[88:89]
	v_pk_mul_f32 v[90:91], v[90:91], v[90:91]
	v_pk_mul_f32 v[92:93], v[154:155], v[92:93]
	v_pk_mul_f32 v[94:95], v[154:155], v[94:95]
	v_pk_mul_f32 v[88:89], v[154:155], v[88:89]
	v_pk_mul_f32 v[90:91], v[154:155], v[90:91]
	v_add_f32_e32 v194, v228, v92
	v_add_f32_e32 v195, v228, v88
	v_add_f32_sdwa v194, v93, v228 dst_sel:BYTE_1 dst_unused:UNUSED_PRESERVE src0_sel:DWORD src1_sel:DWORD
	v_add_f32_sdwa v195, v89, v228 dst_sel:BYTE_1 dst_unused:UNUSED_PRESERVE src0_sel:DWORD src1_sel:DWORD
	v_add_f32_sdwa v194, v94, v228 dst_sel:BYTE_2 dst_unused:UNUSED_PRESERVE src0_sel:DWORD src1_sel:DWORD
	v_add_f32_sdwa v195, v90, v228 dst_sel:BYTE_2 dst_unused:UNUSED_PRESERVE src0_sel:DWORD src1_sel:DWORD
	v_add_f32_sdwa v194, v95, v228 dst_sel:BYTE_3 dst_unused:UNUSED_PRESERVE src0_sel:DWORD src1_sel:DWORD
	v_add_f32_sdwa v195, v91, v228 dst_sel:BYTE_3 dst_unused:UNUSED_PRESERVE src0_sel:DWORD src1_sel:DWORD
	v_xor_b32_e32 v194, s55, v194
	v_xor_b32_e32 v195, s55, v195
	global_store_dwordx2 v[152:153], v[194:195], off
	v_cvt_f32_i32_e32 v84, v84
	v_cvt_f32_i32_e32 v85, v85
	v_cvt_f32_i32_e32 v86, v86
	v_cvt_f32_i32_e32 v87, v87
	v_cvt_f32_i32_e32 v80, v80
	v_cvt_f32_i32_e32 v81, v81
	v_cvt_f32_i32_e32 v82, v82
	v_cvt_f32_i32_e32 v83, v83
	v_pk_mul_f32 v[84:85], v[236:237], v[84:85] op_sel_hi:[0,1]
	v_pk_mul_f32 v[86:87], v[236:237], v[86:87] op_sel_hi:[0,1]
	v_pk_mul_f32 v[80:81], v[236:237], v[80:81] op_sel_hi:[0,1]
	v_pk_mul_f32 v[82:83], v[236:237], v[82:83] op_sel_hi:[0,1]
	v_max_f32_e32 v84, 0, v84
	v_max_f32_e32 v85, 0, v85
	v_max_f32_e32 v86, 0, v86
	v_max_f32_e32 v87, 0, v87
	v_max_f32_e32 v80, 0, v80
	v_max_f32_e32 v81, 0, v81
	v_max_f32_e32 v82, 0, v82
	v_max_f32_e32 v83, 0, v83
	v_pk_mul_f32 v[84:85], v[84:85], v[84:85]
	v_pk_mul_f32 v[86:87], v[86:87], v[86:87]
	v_pk_mul_f32 v[80:81], v[80:81], v[80:81]
	v_pk_mul_f32 v[82:83], v[82:83], v[82:83]
	v_pk_mul_f32 v[84:85], v[154:155], v[84:85]
	v_pk_mul_f32 v[86:87], v[154:155], v[86:87]
	v_pk_mul_f32 v[80:81], v[154:155], v[80:81]
	v_pk_mul_f32 v[82:83], v[154:155], v[82:83]
	v_add_f32_e32 v196, v228, v84
	v_add_f32_e32 v197, v228, v80
	v_add_f32_sdwa v196, v85, v228 dst_sel:BYTE_1 dst_unused:UNUSED_PRESERVE src0_sel:DWORD src1_sel:DWORD
	v_add_f32_sdwa v197, v81, v228 dst_sel:BYTE_1 dst_unused:UNUSED_PRESERVE src0_sel:DWORD src1_sel:DWORD
	v_add_f32_sdwa v196, v86, v228 dst_sel:BYTE_2 dst_unused:UNUSED_PRESERVE src0_sel:DWORD src1_sel:DWORD
	v_add_f32_sdwa v197, v82, v228 dst_sel:BYTE_2 dst_unused:UNUSED_PRESERVE src0_sel:DWORD src1_sel:DWORD
	v_add_f32_sdwa v196, v87, v228 dst_sel:BYTE_3 dst_unused:UNUSED_PRESERVE src0_sel:DWORD src1_sel:DWORD
	v_add_f32_sdwa v197, v83, v228 dst_sel:BYTE_3 dst_unused:UNUSED_PRESERVE src0_sel:DWORD src1_sel:DWORD
	v_xor_b32_e32 v196, s55, v196
	v_xor_b32_e32 v197, s55, v197
	global_store_dwordx2 v[152:153], v[196:197], off offset:128
	v_add_co_u32_e32 v152, vcc, 0xc0000, v150
	s_nop 1
	v_addc_co_u32_e32 v153, vcc, 0, v151, vcc
	v_cvt_f32_i32_e32 v76, v76
	v_cvt_f32_i32_e32 v77, v77
	v_cvt_f32_i32_e32 v78, v78
	v_cvt_f32_i32_e32 v79, v79
	v_cvt_f32_i32_e32 v72, v72
	v_cvt_f32_i32_e32 v73, v73
	v_cvt_f32_i32_e32 v74, v74
	v_cvt_f32_i32_e32 v75, v75
	v_pk_mul_f32 v[76:77], v[238:239], v[76:77] op_sel_hi:[0,1]
	v_pk_mul_f32 v[78:79], v[238:239], v[78:79] op_sel_hi:[0,1]
	v_pk_mul_f32 v[72:73], v[238:239], v[72:73] op_sel_hi:[0,1]
	v_pk_mul_f32 v[74:75], v[238:239], v[74:75] op_sel_hi:[0,1]
	v_max_f32_e32 v76, 0, v76
	v_max_f32_e32 v77, 0, v77
	v_max_f32_e32 v78, 0, v78
	v_max_f32_e32 v79, 0, v79
	v_max_f32_e32 v72, 0, v72
	v_max_f32_e32 v73, 0, v73
	v_max_f32_e32 v74, 0, v74
	v_max_f32_e32 v75, 0, v75
	v_pk_mul_f32 v[76:77], v[76:77], v[76:77]
	v_pk_mul_f32 v[78:79], v[78:79], v[78:79]
	v_pk_mul_f32 v[72:73], v[72:73], v[72:73]
	v_pk_mul_f32 v[74:75], v[74:75], v[74:75]
	v_pk_mul_f32 v[76:77], v[154:155], v[76:77]
	v_pk_mul_f32 v[78:79], v[154:155], v[78:79]
	v_pk_mul_f32 v[72:73], v[154:155], v[72:73]
	v_pk_mul_f32 v[74:75], v[154:155], v[74:75]
	v_add_f32_e32 v198, v228, v76
	v_add_f32_e32 v199, v228, v72
	v_add_f32_sdwa v198, v77, v228 dst_sel:BYTE_1 dst_unused:UNUSED_PRESERVE src0_sel:DWORD src1_sel:DWORD
	v_add_f32_sdwa v199, v73, v228 dst_sel:BYTE_1 dst_unused:UNUSED_PRESERVE src0_sel:DWORD src1_sel:DWORD
	v_add_f32_sdwa v198, v78, v228 dst_sel:BYTE_2 dst_unused:UNUSED_PRESERVE src0_sel:DWORD src1_sel:DWORD
	v_add_f32_sdwa v199, v74, v228 dst_sel:BYTE_2 dst_unused:UNUSED_PRESERVE src0_sel:DWORD src1_sel:DWORD
	v_add_f32_sdwa v198, v79, v228 dst_sel:BYTE_3 dst_unused:UNUSED_PRESERVE src0_sel:DWORD src1_sel:DWORD
	v_add_f32_sdwa v199, v75, v228 dst_sel:BYTE_3 dst_unused:UNUSED_PRESERVE src0_sel:DWORD src1_sel:DWORD
	v_xor_b32_e32 v198, s55, v198
	v_xor_b32_e32 v199, s55, v199
	global_store_dwordx2 v[152:153], v[198:199], off
	v_cvt_f32_i32_e32 v68, v68
	v_cvt_f32_i32_e32 v69, v69
	v_cvt_f32_i32_e32 v70, v70
	v_cvt_f32_i32_e32 v71, v71
	v_cvt_f32_i32_e32 v64, v64
	v_cvt_f32_i32_e32 v65, v65
	v_cvt_f32_i32_e32 v66, v66
	v_cvt_f32_i32_e32 v67, v67
	v_pk_mul_f32 v[68:69], v[238:239], v[68:69] op_sel_hi:[0,1]
	v_pk_mul_f32 v[70:71], v[238:239], v[70:71] op_sel_hi:[0,1]
	v_pk_mul_f32 v[64:65], v[238:239], v[64:65] op_sel_hi:[0,1]
	v_pk_mul_f32 v[66:67], v[238:239], v[66:67] op_sel_hi:[0,1]
	v_max_f32_e32 v68, 0, v68
	v_max_f32_e32 v69, 0, v69
	v_max_f32_e32 v70, 0, v70
	v_max_f32_e32 v71, 0, v71
	v_max_f32_e32 v64, 0, v64
	v_max_f32_e32 v65, 0, v65
	v_max_f32_e32 v66, 0, v66
	v_max_f32_e32 v67, 0, v67
	v_pk_mul_f32 v[68:69], v[68:69], v[68:69]
	v_pk_mul_f32 v[70:71], v[70:71], v[70:71]
	v_pk_mul_f32 v[64:65], v[64:65], v[64:65]
	v_pk_mul_f32 v[66:67], v[66:67], v[66:67]
	v_pk_mul_f32 v[68:69], v[154:155], v[68:69]
	v_pk_mul_f32 v[70:71], v[154:155], v[70:71]
	v_pk_mul_f32 v[64:65], v[154:155], v[64:65]
	v_pk_mul_f32 v[66:67], v[154:155], v[66:67]
	v_add_f32_e32 v200, v228, v68
	v_add_f32_e32 v201, v228, v64
	v_add_f32_sdwa v200, v69, v228 dst_sel:BYTE_1 dst_unused:UNUSED_PRESERVE src0_sel:DWORD src1_sel:DWORD
	v_add_f32_sdwa v201, v65, v228 dst_sel:BYTE_1 dst_unused:UNUSED_PRESERVE src0_sel:DWORD src1_sel:DWORD
	v_add_f32_sdwa v200, v70, v228 dst_sel:BYTE_2 dst_unused:UNUSED_PRESERVE src0_sel:DWORD src1_sel:DWORD
	v_add_f32_sdwa v201, v66, v228 dst_sel:BYTE_2 dst_unused:UNUSED_PRESERVE src0_sel:DWORD src1_sel:DWORD
	v_add_f32_sdwa v200, v71, v228 dst_sel:BYTE_3 dst_unused:UNUSED_PRESERVE src0_sel:DWORD src1_sel:DWORD
	v_add_f32_sdwa v201, v67, v228 dst_sel:BYTE_3 dst_unused:UNUSED_PRESERVE src0_sel:DWORD src1_sel:DWORD
	v_xor_b32_e32 v200, s55, v200
	v_xor_b32_e32 v201, s55, v201
	global_store_dwordx2 v[152:153], v[200:201], off offset:128
	v_add_co_u32_e32 v152, vcc, 0x200000, v150
	s_nop 1
	v_addc_co_u32_e32 v153, vcc, 0, v151, vcc
	v_cvt_f32_i32_e32 v60, v60
	v_cvt_f32_i32_e32 v61, v61
	v_cvt_f32_i32_e32 v62, v62
	v_cvt_f32_i32_e32 v63, v63
	v_cvt_f32_i32_e32 v56, v56
	v_cvt_f32_i32_e32 v57, v57
	v_cvt_f32_i32_e32 v58, v58
	v_cvt_f32_i32_e32 v59, v59
	v_pk_mul_f32 v[60:61], v[240:241], v[60:61] op_sel_hi:[0,1]
	v_pk_mul_f32 v[62:63], v[240:241], v[62:63] op_sel_hi:[0,1]
	v_pk_mul_f32 v[56:57], v[240:241], v[56:57] op_sel_hi:[0,1]
	v_pk_mul_f32 v[58:59], v[240:241], v[58:59] op_sel_hi:[0,1]
	v_max_f32_e32 v60, 0, v60
	v_max_f32_e32 v61, 0, v61
	v_max_f32_e32 v62, 0, v62
	v_max_f32_e32 v63, 0, v63
	v_max_f32_e32 v56, 0, v56
	v_max_f32_e32 v57, 0, v57
	v_max_f32_e32 v58, 0, v58
	v_max_f32_e32 v59, 0, v59
	v_pk_mul_f32 v[60:61], v[60:61], v[60:61]
	v_pk_mul_f32 v[62:63], v[62:63], v[62:63]
	v_pk_mul_f32 v[56:57], v[56:57], v[56:57]
	v_pk_mul_f32 v[58:59], v[58:59], v[58:59]
	v_pk_mul_f32 v[60:61], v[154:155], v[60:61]
	v_pk_mul_f32 v[62:63], v[154:155], v[62:63]
	v_pk_mul_f32 v[56:57], v[154:155], v[56:57]
	v_pk_mul_f32 v[58:59], v[154:155], v[58:59]
	v_add_f32_e32 v186, v228, v60
	v_add_f32_e32 v187, v228, v56
	v_add_f32_sdwa v186, v61, v228 dst_sel:BYTE_1 dst_unused:UNUSED_PRESERVE src0_sel:DWORD src1_sel:DWORD
	v_add_f32_sdwa v187, v57, v228 dst_sel:BYTE_1 dst_unused:UNUSED_PRESERVE src0_sel:DWORD src1_sel:DWORD
	v_add_f32_sdwa v186, v62, v228 dst_sel:BYTE_2 dst_unused:UNUSED_PRESERVE src0_sel:DWORD src1_sel:DWORD
	v_add_f32_sdwa v187, v58, v228 dst_sel:BYTE_2 dst_unused:UNUSED_PRESERVE src0_sel:DWORD src1_sel:DWORD
	v_add_f32_sdwa v186, v63, v228 dst_sel:BYTE_3 dst_unused:UNUSED_PRESERVE src0_sel:DWORD src1_sel:DWORD
	v_add_f32_sdwa v187, v59, v228 dst_sel:BYTE_3 dst_unused:UNUSED_PRESERVE src0_sel:DWORD src1_sel:DWORD
	v_xor_b32_e32 v186, s55, v186
	v_xor_b32_e32 v187, s55, v187
	global_store_dwordx2 v[152:153], v[186:187], off
	v_cvt_f32_i32_e32 v52, v52
	v_cvt_f32_i32_e32 v53, v53
	v_cvt_f32_i32_e32 v54, v54
	v_cvt_f32_i32_e32 v55, v55
	v_cvt_f32_i32_e32 v48, v48
	v_cvt_f32_i32_e32 v49, v49
	v_cvt_f32_i32_e32 v50, v50
	v_cvt_f32_i32_e32 v51, v51
	v_pk_mul_f32 v[52:53], v[240:241], v[52:53] op_sel_hi:[0,1]
	v_pk_mul_f32 v[54:55], v[240:241], v[54:55] op_sel_hi:[0,1]
	v_pk_mul_f32 v[48:49], v[240:241], v[48:49] op_sel_hi:[0,1]
	v_pk_mul_f32 v[50:51], v[240:241], v[50:51] op_sel_hi:[0,1]
	v_max_f32_e32 v52, 0, v52
	v_max_f32_e32 v53, 0, v53
	v_max_f32_e32 v54, 0, v54
	v_max_f32_e32 v55, 0, v55
	v_max_f32_e32 v48, 0, v48
	v_max_f32_e32 v49, 0, v49
	v_max_f32_e32 v50, 0, v50
	v_max_f32_e32 v51, 0, v51
	v_pk_mul_f32 v[52:53], v[52:53], v[52:53]
	v_pk_mul_f32 v[54:55], v[54:55], v[54:55]
	v_pk_mul_f32 v[48:49], v[48:49], v[48:49]
	v_pk_mul_f32 v[50:51], v[50:51], v[50:51]
	v_pk_mul_f32 v[52:53], v[154:155], v[52:53]
	v_pk_mul_f32 v[54:55], v[154:155], v[54:55]
	v_pk_mul_f32 v[48:49], v[154:155], v[48:49]
	v_pk_mul_f32 v[50:51], v[154:155], v[50:51]
	v_add_f32_e32 v188, v228, v52
	v_add_f32_e32 v189, v228, v48
	v_add_f32_sdwa v188, v53, v228 dst_sel:BYTE_1 dst_unused:UNUSED_PRESERVE src0_sel:DWORD src1_sel:DWORD
	v_add_f32_sdwa v189, v49, v228 dst_sel:BYTE_1 dst_unused:UNUSED_PRESERVE src0_sel:DWORD src1_sel:DWORD
	v_add_f32_sdwa v188, v54, v228 dst_sel:BYTE_2 dst_unused:UNUSED_PRESERVE src0_sel:DWORD src1_sel:DWORD
	v_add_f32_sdwa v189, v50, v228 dst_sel:BYTE_2 dst_unused:UNUSED_PRESERVE src0_sel:DWORD src1_sel:DWORD
	v_add_f32_sdwa v188, v55, v228 dst_sel:BYTE_3 dst_unused:UNUSED_PRESERVE src0_sel:DWORD src1_sel:DWORD
	v_add_f32_sdwa v189, v51, v228 dst_sel:BYTE_3 dst_unused:UNUSED_PRESERVE src0_sel:DWORD src1_sel:DWORD
	v_xor_b32_e32 v188, s55, v188
	v_xor_b32_e32 v189, s55, v189
	global_store_dwordx2 v[152:153], v[188:189], off offset:128
	v_add_co_u32_e32 v152, vcc, 0x240000, v150
	s_nop 1
	v_addc_co_u32_e32 v153, vcc, 0, v151, vcc
	v_cvt_f32_i32_e32 v44, v44
	v_cvt_f32_i32_e32 v45, v45
	v_cvt_f32_i32_e32 v46, v46
	v_cvt_f32_i32_e32 v47, v47
	v_cvt_f32_i32_e32 v40, v40
	v_cvt_f32_i32_e32 v41, v41
	v_cvt_f32_i32_e32 v42, v42
	v_cvt_f32_i32_e32 v43, v43
	v_pk_mul_f32 v[44:45], v[242:243], v[44:45] op_sel_hi:[0,1]
	v_pk_mul_f32 v[46:47], v[242:243], v[46:47] op_sel_hi:[0,1]
	v_pk_mul_f32 v[40:41], v[242:243], v[40:41] op_sel_hi:[0,1]
	v_pk_mul_f32 v[42:43], v[242:243], v[42:43] op_sel_hi:[0,1]
	v_max_f32_e32 v44, 0, v44
	v_max_f32_e32 v45, 0, v45
	v_max_f32_e32 v46, 0, v46
	v_max_f32_e32 v47, 0, v47
	v_max_f32_e32 v40, 0, v40
	v_max_f32_e32 v41, 0, v41
	v_max_f32_e32 v42, 0, v42
	v_max_f32_e32 v43, 0, v43
	v_pk_mul_f32 v[44:45], v[44:45], v[44:45]
	v_pk_mul_f32 v[46:47], v[46:47], v[46:47]
	v_pk_mul_f32 v[40:41], v[40:41], v[40:41]
	v_pk_mul_f32 v[42:43], v[42:43], v[42:43]
	v_pk_mul_f32 v[44:45], v[154:155], v[44:45]
	v_pk_mul_f32 v[46:47], v[154:155], v[46:47]
	v_pk_mul_f32 v[40:41], v[154:155], v[40:41]
	v_pk_mul_f32 v[42:43], v[154:155], v[42:43]
	v_add_f32_e32 v190, v228, v44
	v_add_f32_e32 v191, v228, v40
	v_add_f32_sdwa v190, v45, v228 dst_sel:BYTE_1 dst_unused:UNUSED_PRESERVE src0_sel:DWORD src1_sel:DWORD
	v_add_f32_sdwa v191, v41, v228 dst_sel:BYTE_1 dst_unused:UNUSED_PRESERVE src0_sel:DWORD src1_sel:DWORD
	v_add_f32_sdwa v190, v46, v228 dst_sel:BYTE_2 dst_unused:UNUSED_PRESERVE src0_sel:DWORD src1_sel:DWORD
	v_add_f32_sdwa v191, v42, v228 dst_sel:BYTE_2 dst_unused:UNUSED_PRESERVE src0_sel:DWORD src1_sel:DWORD
	v_add_f32_sdwa v190, v47, v228 dst_sel:BYTE_3 dst_unused:UNUSED_PRESERVE src0_sel:DWORD src1_sel:DWORD
	v_add_f32_sdwa v191, v43, v228 dst_sel:BYTE_3 dst_unused:UNUSED_PRESERVE src0_sel:DWORD src1_sel:DWORD
	v_xor_b32_e32 v190, s55, v190
	v_xor_b32_e32 v191, s55, v191
	global_store_dwordx2 v[152:153], v[190:191], off
	v_cvt_f32_i32_e32 v36, v36
	v_cvt_f32_i32_e32 v37, v37
	v_cvt_f32_i32_e32 v38, v38
	v_cvt_f32_i32_e32 v39, v39
	v_cvt_f32_i32_e32 v32, v32
	v_cvt_f32_i32_e32 v33, v33
	v_cvt_f32_i32_e32 v34, v34
	v_cvt_f32_i32_e32 v35, v35
	v_pk_mul_f32 v[36:37], v[242:243], v[36:37] op_sel_hi:[0,1]
	v_pk_mul_f32 v[38:39], v[242:243], v[38:39] op_sel_hi:[0,1]
	v_pk_mul_f32 v[32:33], v[242:243], v[32:33] op_sel_hi:[0,1]
	v_pk_mul_f32 v[34:35], v[242:243], v[34:35] op_sel_hi:[0,1]
	v_max_f32_e32 v36, 0, v36
	v_max_f32_e32 v37, 0, v37
	v_max_f32_e32 v38, 0, v38
	v_max_f32_e32 v39, 0, v39
	v_max_f32_e32 v32, 0, v32
	v_max_f32_e32 v33, 0, v33
	v_max_f32_e32 v34, 0, v34
	v_max_f32_e32 v35, 0, v35
	v_pk_mul_f32 v[36:37], v[36:37], v[36:37]
	v_pk_mul_f32 v[38:39], v[38:39], v[38:39]
	v_pk_mul_f32 v[32:33], v[32:33], v[32:33]
	v_pk_mul_f32 v[34:35], v[34:35], v[34:35]
	v_pk_mul_f32 v[36:37], v[154:155], v[36:37]
	v_pk_mul_f32 v[38:39], v[154:155], v[38:39]
	v_pk_mul_f32 v[32:33], v[154:155], v[32:33]
	v_pk_mul_f32 v[34:35], v[154:155], v[34:35]
	v_add_f32_e32 v192, v228, v36
	v_add_f32_e32 v193, v228, v32
	v_add_f32_sdwa v192, v37, v228 dst_sel:BYTE_1 dst_unused:UNUSED_PRESERVE src0_sel:DWORD src1_sel:DWORD
	v_add_f32_sdwa v193, v33, v228 dst_sel:BYTE_1 dst_unused:UNUSED_PRESERVE src0_sel:DWORD src1_sel:DWORD
	v_add_f32_sdwa v192, v38, v228 dst_sel:BYTE_2 dst_unused:UNUSED_PRESERVE src0_sel:DWORD src1_sel:DWORD
	v_add_f32_sdwa v193, v34, v228 dst_sel:BYTE_2 dst_unused:UNUSED_PRESERVE src0_sel:DWORD src1_sel:DWORD
	v_add_f32_sdwa v192, v39, v228 dst_sel:BYTE_3 dst_unused:UNUSED_PRESERVE src0_sel:DWORD src1_sel:DWORD
	v_add_f32_sdwa v193, v35, v228 dst_sel:BYTE_3 dst_unused:UNUSED_PRESERVE src0_sel:DWORD src1_sel:DWORD
	v_xor_b32_e32 v192, s55, v192
	v_xor_b32_e32 v193, s55, v193
	global_store_dwordx2 v[152:153], v[192:193], off offset:128
	v_add_co_u32_e32 v152, vcc, 0x280000, v150
	s_nop 1
	v_addc_co_u32_e32 v153, vcc, 0, v151, vcc
	v_cvt_f32_i32_e32 v28, v28
	v_cvt_f32_i32_e32 v29, v29
	v_cvt_f32_i32_e32 v30, v30
	v_cvt_f32_i32_e32 v31, v31
	v_cvt_f32_i32_e32 v24, v24
	v_cvt_f32_i32_e32 v25, v25
	v_cvt_f32_i32_e32 v26, v26
	v_cvt_f32_i32_e32 v27, v27
	v_pk_mul_f32 v[28:29], v[244:245], v[28:29] op_sel_hi:[0,1]
	v_pk_mul_f32 v[30:31], v[244:245], v[30:31] op_sel_hi:[0,1]
	v_pk_mul_f32 v[24:25], v[244:245], v[24:25] op_sel_hi:[0,1]
	v_pk_mul_f32 v[26:27], v[244:245], v[26:27] op_sel_hi:[0,1]
	v_max_f32_e32 v28, 0, v28
	v_max_f32_e32 v29, 0, v29
	v_max_f32_e32 v30, 0, v30
	v_max_f32_e32 v31, 0, v31
	v_max_f32_e32 v24, 0, v24
	v_max_f32_e32 v25, 0, v25
	v_max_f32_e32 v26, 0, v26
	v_max_f32_e32 v27, 0, v27
	v_pk_mul_f32 v[28:29], v[28:29], v[28:29]
	v_pk_mul_f32 v[30:31], v[30:31], v[30:31]
	v_pk_mul_f32 v[24:25], v[24:25], v[24:25]
	v_pk_mul_f32 v[26:27], v[26:27], v[26:27]
	v_pk_mul_f32 v[28:29], v[154:155], v[28:29]
	v_pk_mul_f32 v[30:31], v[154:155], v[30:31]
	v_pk_mul_f32 v[24:25], v[154:155], v[24:25]
	v_pk_mul_f32 v[26:27], v[154:155], v[26:27]
	v_add_f32_e32 v194, v228, v28
	v_add_f32_e32 v195, v228, v24
	v_add_f32_sdwa v194, v29, v228 dst_sel:BYTE_1 dst_unused:UNUSED_PRESERVE src0_sel:DWORD src1_sel:DWORD
	v_add_f32_sdwa v195, v25, v228 dst_sel:BYTE_1 dst_unused:UNUSED_PRESERVE src0_sel:DWORD src1_sel:DWORD
	v_add_f32_sdwa v194, v30, v228 dst_sel:BYTE_2 dst_unused:UNUSED_PRESERVE src0_sel:DWORD src1_sel:DWORD
	v_add_f32_sdwa v195, v26, v228 dst_sel:BYTE_2 dst_unused:UNUSED_PRESERVE src0_sel:DWORD src1_sel:DWORD
	v_add_f32_sdwa v194, v31, v228 dst_sel:BYTE_3 dst_unused:UNUSED_PRESERVE src0_sel:DWORD src1_sel:DWORD
	v_add_f32_sdwa v195, v27, v228 dst_sel:BYTE_3 dst_unused:UNUSED_PRESERVE src0_sel:DWORD src1_sel:DWORD
	v_xor_b32_e32 v194, s55, v194
	v_xor_b32_e32 v195, s55, v195
	global_store_dwordx2 v[152:153], v[194:195], off
	v_cvt_f32_i32_e32 v20, v20
	v_cvt_f32_i32_e32 v21, v21
	v_cvt_f32_i32_e32 v22, v22
	v_cvt_f32_i32_e32 v23, v23
	v_cvt_f32_i32_e32 v16, v16
	v_cvt_f32_i32_e32 v17, v17
	v_cvt_f32_i32_e32 v18, v18
	v_cvt_f32_i32_e32 v19, v19
	v_pk_mul_f32 v[20:21], v[244:245], v[20:21] op_sel_hi:[0,1]
	v_pk_mul_f32 v[22:23], v[244:245], v[22:23] op_sel_hi:[0,1]
	v_pk_mul_f32 v[16:17], v[244:245], v[16:17] op_sel_hi:[0,1]
	v_pk_mul_f32 v[18:19], v[244:245], v[18:19] op_sel_hi:[0,1]
	v_max_f32_e32 v20, 0, v20
	v_max_f32_e32 v21, 0, v21
	v_max_f32_e32 v22, 0, v22
	v_max_f32_e32 v23, 0, v23
	v_max_f32_e32 v16, 0, v16
	v_max_f32_e32 v17, 0, v17
	v_max_f32_e32 v18, 0, v18
	v_max_f32_e32 v19, 0, v19
	v_pk_mul_f32 v[20:21], v[20:21], v[20:21]
	v_pk_mul_f32 v[22:23], v[22:23], v[22:23]
	v_pk_mul_f32 v[16:17], v[16:17], v[16:17]
	v_pk_mul_f32 v[18:19], v[18:19], v[18:19]
	v_pk_mul_f32 v[20:21], v[154:155], v[20:21]
	v_pk_mul_f32 v[22:23], v[154:155], v[22:23]
	v_pk_mul_f32 v[16:17], v[154:155], v[16:17]
	v_pk_mul_f32 v[18:19], v[154:155], v[18:19]
	v_add_f32_e32 v196, v228, v20
	v_add_f32_e32 v197, v228, v16
	v_add_f32_sdwa v196, v21, v228 dst_sel:BYTE_1 dst_unused:UNUSED_PRESERVE src0_sel:DWORD src1_sel:DWORD
	v_add_f32_sdwa v197, v17, v228 dst_sel:BYTE_1 dst_unused:UNUSED_PRESERVE src0_sel:DWORD src1_sel:DWORD
	v_add_f32_sdwa v196, v22, v228 dst_sel:BYTE_2 dst_unused:UNUSED_PRESERVE src0_sel:DWORD src1_sel:DWORD
	v_add_f32_sdwa v197, v18, v228 dst_sel:BYTE_2 dst_unused:UNUSED_PRESERVE src0_sel:DWORD src1_sel:DWORD
	v_add_f32_sdwa v196, v23, v228 dst_sel:BYTE_3 dst_unused:UNUSED_PRESERVE src0_sel:DWORD src1_sel:DWORD
	v_add_f32_sdwa v197, v19, v228 dst_sel:BYTE_3 dst_unused:UNUSED_PRESERVE src0_sel:DWORD src1_sel:DWORD
	v_xor_b32_e32 v196, s55, v196
	v_xor_b32_e32 v197, s55, v197
	global_store_dwordx2 v[152:153], v[196:197], off offset:128
	v_add_co_u32_e32 v152, vcc, 0x2c0000, v150
	s_nop 1
	v_addc_co_u32_e32 v153, vcc, 0, v151, vcc
	v_cvt_f32_i32_e32 v12, v12
	v_cvt_f32_i32_e32 v13, v13
	v_cvt_f32_i32_e32 v14, v14
	v_cvt_f32_i32_e32 v15, v15
	v_cvt_f32_i32_e32 v8, v8
	v_cvt_f32_i32_e32 v9, v9
	v_cvt_f32_i32_e32 v10, v10
	v_cvt_f32_i32_e32 v11, v11
	v_pk_mul_f32 v[12:13], v[246:247], v[12:13] op_sel_hi:[0,1]
	v_pk_mul_f32 v[14:15], v[246:247], v[14:15] op_sel_hi:[0,1]
	v_pk_mul_f32 v[8:9], v[246:247], v[8:9] op_sel_hi:[0,1]
	v_pk_mul_f32 v[10:11], v[246:247], v[10:11] op_sel_hi:[0,1]
	v_max_f32_e32 v12, 0, v12
	v_max_f32_e32 v13, 0, v13
	v_max_f32_e32 v14, 0, v14
	v_max_f32_e32 v15, 0, v15
	v_max_f32_e32 v8, 0, v8
	v_max_f32_e32 v9, 0, v9
	v_max_f32_e32 v10, 0, v10
	v_max_f32_e32 v11, 0, v11
	v_pk_mul_f32 v[12:13], v[12:13], v[12:13]
	v_pk_mul_f32 v[14:15], v[14:15], v[14:15]
	v_pk_mul_f32 v[8:9], v[8:9], v[8:9]
	v_pk_mul_f32 v[10:11], v[10:11], v[10:11]
	v_pk_mul_f32 v[12:13], v[154:155], v[12:13]
	v_pk_mul_f32 v[14:15], v[154:155], v[14:15]
	v_pk_mul_f32 v[8:9], v[154:155], v[8:9]
	v_pk_mul_f32 v[10:11], v[154:155], v[10:11]
	v_add_f32_e32 v198, v228, v12
	v_add_f32_e32 v199, v228, v8
	v_add_f32_sdwa v198, v13, v228 dst_sel:BYTE_1 dst_unused:UNUSED_PRESERVE src0_sel:DWORD src1_sel:DWORD
	v_add_f32_sdwa v199, v9, v228 dst_sel:BYTE_1 dst_unused:UNUSED_PRESERVE src0_sel:DWORD src1_sel:DWORD
	v_add_f32_sdwa v198, v14, v228 dst_sel:BYTE_2 dst_unused:UNUSED_PRESERVE src0_sel:DWORD src1_sel:DWORD
	v_add_f32_sdwa v199, v10, v228 dst_sel:BYTE_2 dst_unused:UNUSED_PRESERVE src0_sel:DWORD src1_sel:DWORD
	v_add_f32_sdwa v198, v15, v228 dst_sel:BYTE_3 dst_unused:UNUSED_PRESERVE src0_sel:DWORD src1_sel:DWORD
	v_add_f32_sdwa v199, v11, v228 dst_sel:BYTE_3 dst_unused:UNUSED_PRESERVE src0_sel:DWORD src1_sel:DWORD
	v_xor_b32_e32 v198, s55, v198
	v_xor_b32_e32 v199, s55, v199
	global_store_dwordx2 v[152:153], v[198:199], off
	v_cvt_f32_i32_e32 v4, v4
	v_cvt_f32_i32_e32 v5, v5
	v_cvt_f32_i32_e32 v6, v6
	v_cvt_f32_i32_e32 v7, v7
	v_cvt_f32_i32_e32 v0, v0
	v_cvt_f32_i32_e32 v1, v1
	v_cvt_f32_i32_e32 v2, v2
	v_cvt_f32_i32_e32 v3, v3
	v_pk_mul_f32 v[4:5], v[246:247], v[4:5] op_sel_hi:[0,1]
	v_pk_mul_f32 v[6:7], v[246:247], v[6:7] op_sel_hi:[0,1]
	v_pk_mul_f32 v[0:1], v[246:247], v[0:1] op_sel_hi:[0,1]
	v_pk_mul_f32 v[2:3], v[246:247], v[2:3] op_sel_hi:[0,1]
	v_max_f32_e32 v4, 0, v4
	v_max_f32_e32 v5, 0, v5
	v_max_f32_e32 v6, 0, v6
	v_max_f32_e32 v7, 0, v7
	v_max_f32_e32 v0, 0, v0
	v_max_f32_e32 v1, 0, v1
	v_max_f32_e32 v2, 0, v2
	v_max_f32_e32 v3, 0, v3
	v_pk_mul_f32 v[4:5], v[4:5], v[4:5]
	v_pk_mul_f32 v[6:7], v[6:7], v[6:7]
	v_pk_mul_f32 v[0:1], v[0:1], v[0:1]
	v_pk_mul_f32 v[2:3], v[2:3], v[2:3]
	v_pk_mul_f32 v[4:5], v[154:155], v[4:5]
	v_pk_mul_f32 v[6:7], v[154:155], v[6:7]
	v_pk_mul_f32 v[0:1], v[154:155], v[0:1]
	v_pk_mul_f32 v[2:3], v[154:155], v[2:3]
	v_add_f32_e32 v200, v228, v4
	v_add_f32_e32 v201, v228, v0
	v_add_f32_sdwa v200, v5, v228 dst_sel:BYTE_1 dst_unused:UNUSED_PRESERVE src0_sel:DWORD src1_sel:DWORD
	v_add_f32_sdwa v201, v1, v228 dst_sel:BYTE_1 dst_unused:UNUSED_PRESERVE src0_sel:DWORD src1_sel:DWORD
	v_add_f32_sdwa v200, v6, v228 dst_sel:BYTE_2 dst_unused:UNUSED_PRESERVE src0_sel:DWORD src1_sel:DWORD
	v_add_f32_sdwa v201, v2, v228 dst_sel:BYTE_2 dst_unused:UNUSED_PRESERVE src0_sel:DWORD src1_sel:DWORD
	v_add_f32_sdwa v200, v7, v228 dst_sel:BYTE_3 dst_unused:UNUSED_PRESERVE src0_sel:DWORD src1_sel:DWORD
	v_add_f32_sdwa v201, v3, v228 dst_sel:BYTE_3 dst_unused:UNUSED_PRESERVE src0_sel:DWORD src1_sel:DWORD
	v_xor_b32_e32 v200, s55, v200
	v_xor_b32_e32 v201, s55, v201
	global_store_dwordx2 v[152:153], v[200:201], off offset:128
	s_andn2_b64 vcc, exec, s[2:3]
	s_mov_b64 s[0:1], -1
	s_cbranch_vccnz .LBB0_1348
	s_branch .Ljoin_p11
